# noprio + FFN-up epilogue row scale via v_rsq_f32 instead of sqrt+div ladder
# speedup vs baseline: 1.0839x; 1.0036x over previous
.LBB0_1370:
	s_and_b32 s9, s9, 1
	s_lshl_b32 s4, s9, 11
	v_mov_b32_e32 v222, v230
	v_mov_b32_e32 v239, v231
	s_add_i32 s4, s91, s4
	v_cvt_f32_i32_e32 v199, v127
	v_lshl_add_u32 v134, v222, 4, s4
	ds_read_b128 v[130:133], v134
	v_cvt_f32_i32_e32 v198, v126
	v_cvt_f32_i32_e32 v203, v129
	v_cvt_f32_i32_e32 v202, v128
	v_cvt_f32_i32_e32 v197, v123
	s_waitcnt lgkmcnt(0)
	v_fmamk_f32 v130, v130, 0x39800000, v237
	v_cvt_f32_i32_e32 v196, v122
	v_cvt_f32_i32_e32 v201, v125
	v_cvt_f32_i32_e32 v200, v124
	v_cmp_eq_u32_e64 s[6:7], 15, v222
	v_rsq_f32_e32 v136, v130
	v_fmamk_f32 v130, v131, 0x39800000, v237
	v_rsq_f32_e32 v137, v130
	v_fmamk_f32 v130, v132, 0x39800000, v237
	v_rsq_f32_e32 v162, v130
	v_fmamk_f32 v130, v133, 0x39800000, v237
	v_rsq_f32_e32 v163, v130
	ds_read_b128 v[130:133], v134 offset:1024
	s_waitcnt lgkmcnt(0)
	v_pk_mul_f32 v[164:165], v[132:133], v[162:163]
	v_pk_mul_f32 v[162:163], v[130:131], v[136:137]
	ds_read_b128 v[130:133], v134 offset:512
	ds_read_b128 v[134:137], v134 offset:1536
	s_and_saveexec_b64 s[4:5], s[6:7]
	s_cbranch_execz .LBB0_1372
	v_pk_mul_f32 v[124:125], v[164:165], v[202:203] op_sel_hi:[0,1]
	v_pk_mul_f32 v[122:123], v[164:165], v[198:199] op_sel_hi:[0,1]
	v_lshl_add_u32 v126, v239, 5, s93
	ds_write_b128 v126, v[122:125]
	v_mov_b32_e32 v122, v165
	v_pk_mul_f32 v[124:125], v[122:123], v[200:201] op_sel_hi:[0,1]
	v_pk_mul_f32 v[122:123], v[122:123], v[196:197] op_sel_hi:[0,1]
	ds_write_b128 v126, v[122:125] offset:16

.LBB0_1386:
	s_or_b64 exec, exec, s[18:19]
	s_waitcnt lgkmcnt(0)
	v_fmamk_f32 v66, v130, 0x39800000, v237
	v_rsq_f32_e32 v66, v66
	v_fmamk_f32 v67, v131, 0x39800000, v237
	v_rsq_f32_e32 v67, v67
	v_fmamk_f32 v68, v132, 0x39800000, v237
	v_pk_mul_f32 v[130:131], v[134:135], v[66:67]
	v_cvt_f32_i32_e32 v135, v63
	v_cvt_f32_i32_e32 v134, v62
	v_cndmask_b32_e64 v66, 0, 1, s[12:13]
	v_rsq_f32_e32 v68, v68
	v_fmamk_f32 v69, v133, 0x39800000, v237
	v_cmp_ne_u32_e64 s[4:5], 1, v66
	v_rsq_f32_e32 v69, v69
	s_nop 0
	v_pk_mul_f32 v[132:133], v[136:137], v[68:69]
	v_cvt_f32_i32_e32 v137, v65
	v_cvt_f32_i32_e32 v136, v64
	s_and_saveexec_b64 s[18:19], s[6:7]
	s_cbranch_execz .LBB0_1403
	v_add_lshl_u32 v66, s47, v106, 4
	v_add_u32_e32 v68, 0, v66
	v_mov_b32_e32 v67, v132
	v_pk_mul_f32 v[64:65], v[132:133], v[136:137] op_sel_hi:[0,1]
	v_pk_mul_f32 v[62:63], v[132:133], v[134:135] op_sel_hi:[0,1]
	v_add_u32_e32 v68, 0x20c00, v68
	s_and_b64 vcc, exec, s[4:5]
	ds_write_b128 v68, v[62:65]
	s_cbranch_vccnz .LBB0_1389
	s_lshl_b64 s[6:7], s[42:43], 2
	s_add_u32 s6, s94, s6
	s_addc_u32 s7, s95, s7
	v_lshl_add_u64 v[68:69], v[204:205], 2, s[6:7]
	global_load_dwordx4 v[68:71], v[68:69], off
	s_add_u32 s6, s71, s56
	s_addc_u32 s7, s72, s35
	s_waitcnt vmcnt(0)
	v_pk_mul_f32 v[64:65], v[64:65], v[70:71]
	v_pk_mul_f32 v[62:63], v[62:63], v[68:69]
	v_lshl_add_u64 v[68:69], v[186:187], 2, s[6:7]
	global_store_dwordx4 v[68:69], v[62:65], off

.LBB0_2059:
	s_and_b32 s29, s41, 1
	s_lshl_b32 s2, s29, 11
	v_mov_b32_e32 v239, v231
	v_mov_b32_e32 v222, v230
	s_add_i32 s2, s76, s2
	v_cvt_f32_i32_e32 v199, v127
	v_lshl_add_u32 v134, v222, 4, s2
	ds_read_b128 v[130:133], v134
	v_cvt_f32_i32_e32 v198, v126
	v_cvt_f32_i32_e32 v203, v129
	v_cvt_f32_i32_e32 v202, v128
	v_cvt_f32_i32_e32 v197, v123
	s_waitcnt lgkmcnt(0)
	v_fmamk_f32 v130, v130, 0x39800000, v237
	v_cvt_f32_i32_e32 v196, v122
	v_cvt_f32_i32_e32 v201, v125
	v_cvt_f32_i32_e32 v200, v124
	v_cmp_eq_u32_e64 s[4:5], 15, v222
	v_rsq_f32_e32 v136, v130
	v_fmamk_f32 v130, v131, 0x39800000, v237
	v_rsq_f32_e32 v137, v130
	v_fmamk_f32 v130, v132, 0x39800000, v237
	v_rsq_f32_e32 v162, v130
	v_fmamk_f32 v130, v133, 0x39800000, v237
	v_rsq_f32_e32 v163, v130
	ds_read_b128 v[130:133], v134 offset:1024
	s_waitcnt lgkmcnt(0)
	v_pk_mul_f32 v[164:165], v[132:133], v[162:163]
	v_pk_mul_f32 v[162:163], v[130:131], v[136:137]
	ds_read_b128 v[130:133], v134 offset:512
	ds_read_b128 v[134:137], v134 offset:1536
	s_and_saveexec_b64 s[2:3], s[4:5]
	s_mov_b32 s92, s97
	s_cbranch_execz .LBB0_2061
	v_pk_mul_f32 v[124:125], v[164:165], v[202:203] op_sel_hi:[0,1]
	v_pk_mul_f32 v[122:123], v[164:165], v[198:199] op_sel_hi:[0,1]
	v_lshl_add_u32 v126, v239, 5, s78
	ds_write_b128 v126, v[122:125]
	v_mov_b32_e32 v122, v165
	v_pk_mul_f32 v[124:125], v[122:123], v[200:201] op_sel_hi:[0,1]
	v_pk_mul_f32 v[122:123], v[122:123], v[196:197] op_sel_hi:[0,1]
	ds_write_b128 v126, v[122:125] offset:16

.LBB0_2075:
	s_or_b64 exec, exec, s[18:19]
	s_waitcnt lgkmcnt(0)
	v_fmamk_f32 v66, v130, 0x39800000, v237
	v_rsq_f32_e32 v66, v66
	v_fmamk_f32 v67, v131, 0x39800000, v237
	v_rsq_f32_e32 v67, v67
	v_fmamk_f32 v68, v132, 0x39800000, v237
	v_pk_mul_f32 v[130:131], v[134:135], v[66:67]
	v_cvt_f32_i32_e32 v135, v63
	v_cvt_f32_i32_e32 v134, v62
	v_cndmask_b32_e64 v66, 0, 1, s[10:11]
	v_rsq_f32_e32 v68, v68
	v_fmamk_f32 v69, v133, 0x39800000, v237
	v_cmp_ne_u32_e64 s[2:3], 1, v66
	v_rsq_f32_e32 v69, v69
	s_nop 0
	v_pk_mul_f32 v[132:133], v[136:137], v[68:69]
	v_cvt_f32_i32_e32 v137, v65
	v_cvt_f32_i32_e32 v136, v64
	s_and_saveexec_b64 s[18:19], s[4:5]
	s_cbranch_execz .LBB0_2092
	v_add_lshl_u32 v66, s68, v106, 4
	v_add_u32_e32 v68, 0, v66
	v_mov_b32_e32 v67, v132
	v_pk_mul_f32 v[64:65], v[132:133], v[136:137] op_sel_hi:[0,1]
	v_pk_mul_f32 v[62:63], v[132:133], v[134:135] op_sel_hi:[0,1]
	v_add_u32_e32 v68, 0x20c00, v68
	s_and_b64 vcc, exec, s[2:3]
	ds_write_b128 v68, v[62:65]
	s_cbranch_vccnz .LBB0_2078
	s_lshl_b64 s[4:5], s[40:41], 2
	s_add_u32 s4, s79, s4
	s_addc_u32 s5, s80, s5
	v_lshl_add_u64 v[68:69], v[204:205], 2, s[4:5]
	global_load_dwordx4 v[68:71], v[68:69], off
	s_add_u32 s4, s57, s43
	s_addc_u32 s5, s60, s42
	s_waitcnt vmcnt(0)
	v_pk_mul_f32 v[64:65], v[64:65], v[70:71]
	v_pk_mul_f32 v[62:63], v[62:63], v[68:69]
	v_lshl_add_u64 v[68:69], v[186:187], 2, s[4:5]
	global_store_dwordx4 v[68:69], v[62:65], off
